# v21 + cross-lane conv terms fused into v_fmac_f32_dpp (no separate DPP moves)
# speedup vs baseline: 1.0161x; 1.0002x over previous
; #define LAS __attribute__((address_space(3)))
; #define EPI_LANE() const int lane2 = fresh_lane(), fr = lane2 & 15, fq = lane2 >> 4
;     __device__ __forceinline__ void operator()(const f32x4 (&acc)[2][2][4][2], const Unit& u) const {
;     ...
;             EPI_LANE();
;             const float* cw = P->in[24] + (size_t)layer * 3 * F2; const float* cb = P->in[25] + (size_t)layer * F2;
;             bf16_t* eb = (bf16_t*)(P->ws + WS_EB);
;             const int ch0 = u.pn * 128 + wc * 32 + 8 * fq;
;             const float m0 = fr == 0 ? 1.f : 0.f, n0 = 1.f - m0, m15 = fr == 15 ? 1.f : 0.f, n15 = 1.f - m15;
;             LAS unsigned char* wl = lds + LDS_CW + wid * 1024;
;             { const int a_ = lane2 >> 3, q4 = (lane2 & 7) * 4;
;               const float* src = (a_ < 6 ? cw + (a_ >> 1) * F2 : cb) + (a_ & 1) * F + (unsigned)(u.pn * 128 + wc * 32 + q4);
;               const f32x4 wv = *(const f32x4*)src;
;               *(LAS f32x4*)(wl + lane2 * 16) = wv; }
;             asm volatile("s_waitcnt lgkmcnt(0)" ::: "memory");
; #pragma unroll
;             for (int ai = 0; ai < 2; ++ai) {
;                 const int rowb = u.pm * BM + ai * HALF + wr * 64, q = rowb >> 6;
;                 unsigned gq[4][4], pe[2][2][4];
; #pragma unroll
;                 for (int n = 0; n < 2; ++n) {
;                     f32x4 W[2][4];
; #pragma unroll
;                     for (int part = 0; part < 2; ++part)
; #pragma unroll
;                         for (int k = 0; k < 4; ++k) W[part][k] = *(const LAS f32x4*)(wl + (k * 2 + part) * 128 + (8 * fq + 4 * n) * 4);
; #pragma unroll
;                     for (int ep = 0; ep < 2; ++ep) {
;                         f32x2 cres[2][4];
; #pragma unroll
;                         for (int part = 0; part < 2; ++part) {
;                             const f32x2 w0 = (f32x2){W[part][0][2 * ep], W[part][0][2 * ep + 1]}, w1 = (f32x2){W[part][1][2 * ep], W[part][1][2 * ep + 1]};
;                             const f32x2 w2 = (f32x2){W[part][2][2 * ep], W[part][2][2 * ep + 1]}, bb = (f32x2){W[part][3][2 * ep], W[part][3][2 * ep + 1]};
;                             const f32x2 w0a = w0 * n0, w0b = w0 * m0, w2a = w2 * n15, w2b = w2 * m15;
;                             f32x2 X[4], R[4], L[4];
; #pragma unroll
;                             for (int m = 0; m < 4; ++m) { X[m] = (f32x2){acc[ai][part][m][n][2 * ep], acc[ai][part][m][n][2 * ep + 1]};
.LBB0_346:
	s_and_b64 vcc, exec, s[10:11]
	s_cbranch_vccz .LBB0_373
	s_cmp_eq_u32 s24, 3
	s_mov_b64 s[8:9], -1
	s_cbranch_scc0 .LBB0_373
	v_mbcnt_lo_u32_b32 v130, -1, 0
	v_mbcnt_hi_u32_b32 v130, -1, v130
	s_load_dwordx2 s[10:11], s[6:7], 0xe0
	v_readlane_b32 s3, v255, 12
	v_and_b32_e32 v131, 15, v130
	v_lshrrev_b32_e32 v129, 4, v130
	v_mov_b32_e32 v134, 0xbdd2d3e8
	v_mov_b32_e32 v135, 0xbdd2d3e8
	v_mov_b32_e32 v136, 0xc0135761
	v_mov_b32_e32 v137, 0xc0135761
	v_lshl_add_u32 v132, v129, 5, s3
	v_cmp_eq_u32_e64 s[6:7], 0, v131
	v_cmp_eq_u32_e64 s[8:9], 15, v131
	v_cmp_ne_u32_e64 s[56:57], 0, v131
	v_cmp_ne_u32_e64 s[58:59], 15, v131
	s_lshl_b32 s1, s72, 7
	s_or_b32 s1, s1, s49
	v_lshl_add_u32 v133, v129, 3, s1
	s_lshl_b32 s1, s73, 8
	s_add_i32 s1, s1, s33
	v_lshl_add_u32 v128, v131, 2, s1
	v_mul_lo_u32 v128, v128, s78
	v_lshl_add_u32 v128, v133, 1, v128
	s_lshl_b32 s1, s73, 2
	s_lshr_b32 s3, s33, 6
	s_add_i32 s1, s1, s3
	s_mul_i32 s1, s1, 0x2c0
	v_lshrrev_b32_e32 v129, 3, v133
	v_add_lshl_u32 v129, v129, s1, 6
	v_add_u32_e32 v162, 0x5800, v129
	s_waitcnt lgkmcnt(0)
	s_add_u32 s10, s10, 0x18660000
	s_addc_u32 s11, s11, 0
	ds_read_b64 v[202:203], v132 offset:0
	ds_read_b64 v[204:205], v132 offset:128
	ds_read_b64 v[206:207], v132 offset:256
	ds_read_b64 v[208:209], v132 offset:384
	ds_read_b64 v[210:211], v132 offset:512
	ds_read_b64 v[212:213], v132 offset:640
	ds_read_b64 v[214:215], v132 offset:768
	ds_read_b64 v[216:217], v132 offset:896
	s_waitcnt lgkmcnt(0)
	v_pk_fma_f32 v[234:235], v[116:117], v[206:207], v[214:215]
	v_pk_fma_f32 v[236:237], v[100:101], v[206:207], v[214:215]
	v_pk_fma_f32 v[238:239], v[84:85], v[206:207], v[214:215]
	v_pk_fma_f32 v[240:241], v[52:53], v[206:207], v[214:215]
	v_pk_fma_f32 v[236:237], v[116:117], v[202:203], v[236:237]
	v_pk_fma_f32 v[238:239], v[100:101], v[202:203], v[238:239]
	v_pk_fma_f32 v[240:241], v[84:85], v[202:203], v[240:241]
	v_fmac_f32_dpp v234, v52, v202 row_shr:1 row_mask:0xf bank_mask:0xf bound_ctrl:1
	v_fmac_f32_dpp v235, v53, v203 row_shr:1 row_mask:0xf bank_mask:0xf bound_ctrl:1
	v_pk_fma_f32 v[236:237], v[84:85], v[210:211], v[236:237]
	v_pk_fma_f32 v[238:239], v[52:53], v[210:211], v[238:239]
	v_pk_fma_f32 v[234:235], v[100:101], v[210:211], v[234:235]
	v_fmac_f32_dpp v240, v116, v210 row_shl:1 row_mask:0xf bank_mask:0xf bound_ctrl:1
	v_fmac_f32_dpp v241, v117, v211 row_shl:1 row_mask:0xf bank_mask:0xf bound_ctrl:1
	v_cvt_pk_bf16_f32 v184, v234, v235
	v_cvt_pk_bf16_f32 v192, v240, v241
	v_pk_fma_f32 v[242:243], v[124:125], v[208:209], v[216:217]
	v_pk_fma_f32 v[244:245], v[108:109], v[208:209], v[216:217]
	v_pk_fma_f32 v[246:247], v[92:93], v[208:209], v[216:217]
	v_pk_fma_f32 v[248:249], v[68:69], v[208:209], v[216:217]
	v_pk_fma_f32 v[244:245], v[124:125], v[204:205], v[244:245]
	v_pk_fma_f32 v[246:247], v[108:109], v[204:205], v[246:247]
	v_pk_fma_f32 v[248:249], v[92:93], v[204:205], v[248:249]
	v_fmac_f32_dpp v242, v68, v204 row_shr:1 row_mask:0xf bank_mask:0xf bound_ctrl:1
	v_fmac_f32_dpp v243, v69, v205 row_shr:1 row_mask:0xf bank_mask:0xf bound_ctrl:1
	v_pk_fma_f32 v[244:245], v[92:93], v[212:213], v[244:245]
	v_pk_fma_f32 v[246:247], v[68:69], v[212:213], v[246:247]
	v_pk_fma_f32 v[242:243], v[108:109], v[212:213], v[242:243]
	v_fmac_f32_dpp v248, v124, v212 row_shl:1 row_mask:0xf bank_mask:0xf bound_ctrl:1
	v_fmac_f32_dpp v249, v125, v213 row_shl:1 row_mask:0xf bank_mask:0xf bound_ctrl:1
	v_cvt_pk_bf16_f32 v188, v242, v243
	v_cvt_pk_bf16_f32 v154, v248, v249
	ds_read_b64 v[202:203], v132 offset:8
	ds_read_b64 v[204:205], v132 offset:136
	ds_read_b64 v[206:207], v132 offset:264
	ds_read_b64 v[208:209], v132 offset:392
	ds_read_b64 v[210:211], v132 offset:520
	ds_read_b64 v[212:213], v132 offset:648
	ds_read_b64 v[214:215], v132 offset:776
	ds_read_b64 v[216:217], v132 offset:904
	v_pk_mul_f32 v[138:139], v[234:235], v[234:235]
	v_pk_mul_f32 v[140:141], v[236:237], v[236:237]
	v_pk_mul_f32 v[142:143], v[238:239], v[238:239]
	v_pk_mul_f32 v[144:145], v[240:241], v[240:241]
	v_pk_fma_f32 v[138:139], v[138:139], v[134:135], v[136:137]
	v_pk_fma_f32 v[140:141], v[140:141], v[134:135], v[136:137]
	v_pk_fma_f32 v[142:143], v[142:143], v[134:135], v[136:137]
	v_pk_fma_f32 v[144:145], v[144:145], v[134:135], v[136:137]
	v_pk_mul_f32 v[138:139], v[234:235], v[138:139]
	v_pk_mul_f32 v[140:141], v[236:237], v[140:141]
	v_pk_mul_f32 v[142:143], v[238:239], v[142:143]
	v_pk_mul_f32 v[144:145], v[240:241], v[144:145]
	v_exp_f32_e32 v138, v138
	v_exp_f32_e32 v139, v139
	v_exp_f32_e32 v140, v140
	v_exp_f32_e32 v141, v141
	v_exp_f32_e32 v142, v142
	v_exp_f32_e32 v143, v143
	v_exp_f32_e32 v144, v144
	v_exp_f32_e32 v145, v145
	v_pk_mul_f32 v[146:147], v[234:235], v[242:243]
	v_pk_mul_f32 v[148:149], v[236:237], v[244:245]
	v_pk_mul_f32 v[150:151], v[238:239], v[246:247]
	v_pk_mul_f32 v[152:153], v[240:241], v[248:249]
	v_pk_add_f32 v[138:139], v[138:139], 1.0 op_sel_hi:[1,0]
	v_pk_add_f32 v[140:141], v[140:141], 1.0 op_sel_hi:[1,0]
	v_pk_add_f32 v[142:143], v[142:143], 1.0 op_sel_hi:[1,0]
	v_pk_add_f32 v[144:145], v[144:145], 1.0 op_sel_hi:[1,0]
	v_rcp_f32_e32 v138, v138
	v_rcp_f32_e32 v139, v139
	v_rcp_f32_e32 v140, v140
	v_rcp_f32_e32 v141, v141
	v_rcp_f32_e32 v142, v142
	v_rcp_f32_e32 v143, v143
	v_rcp_f32_e32 v144, v144
	v_rcp_f32_e32 v145, v145
	v_pk_mul_f32 v[146:147], v[146:147], v[138:139]
	v_pk_mul_f32 v[148:149], v[148:149], v[140:141]
	v_pk_mul_f32 v[150:151], v[150:151], v[142:143]
	v_pk_mul_f32 v[152:153], v[152:153], v[144:145]
	v_cvt_pk_bf16_f32 v218, v146, v147
	v_cvt_pk_bf16_f32 v222, v148, v149
	v_cvt_pk_bf16_f32 v226, v150, v151
	v_cvt_pk_bf16_f32 v230, v152, v153
	s_waitcnt lgkmcnt(0)
;     __device__ __forceinline__ void operator()(const f32x4 (&acc)[2][2][4][2], const Unit& u) const {
;     ...
;                     for (int ep = 0; ep < 2; ++ep) {
;                         f32x2 cres[2][4];
; #pragma unroll
;                         for (int part = 0; part < 2; ++part) {
;                             const f32x2 w0 = (f32x2){W[part][0][2 * ep], W[part][0][2 * ep + 1]}, w1 = (f32x2){W[part][1][2 * ep], W[part][1][2 * ep + 1]};
;                             const f32x2 w2 = (f32x2){W[part][2][2 * ep], W[part][2][2 * ep + 1]}, bb = (f32x2){W[part][3][2 * ep], W[part][3][2 * ep + 1]};
;                             const f32x2 w0a = w0 * n0, w0b = w0 * m0, w2a = w2 * n15, w2b = w2 * m15;
;                             f32x2 X[4], R[4], L[4];
; #pragma unroll
;                             for (int m = 0; m < 4; ++m) { X[m] = (f32x2){acc[ai][part][m][n][2 * ep], acc[ai][part][m][n][2 * ep + 1]};
;                                 R[m] = (f32x2){dpp_prev(X[m].x), dpp_prev(X[m].y)}; L[m] = (f32x2){dpp_next(X[m].x), dpp_next(X[m].y)}; }
; #pragma unroll
;                             for (int m = 0; m < 4; ++m) {
;                                 f32x2 c = X[m] * w1 + bb; c = R[m] * w0a + c; c = L[m] * w2a + c;
;                                 if (m > 0) c = R[m > 0 ? m - 1 : 0] * w0b + c;
;                                 if (m < 3) c = L[m < 3 ? m + 1 : 3] * w2b + c;
;                                 cres[part][m] = c;
;                             }
;                             pe[0][part][n * 2 + ep] = cvt_pk_bf16(cres[part][0].x, cres[part][0].y);
;                             pe[1][part][n * 2 + ep] = cvt_pk_bf16(cres[part][3].x, cres[part][3].y);
;                             __builtin_amdgcn_sched_barrier(0);
;                         }
; #pragma unroll
;                         for (int m = 0; m < 4; ++m) {
;                             const f32x2 a = cres[0][m], v = cres[1][m];
;                             const f32x2 t = (a * a) * (-0.10294324f) + (-2.3022082f), z = a * t;
;                             f32x2 d; d.x = __builtin_amdgcn_exp2f(z.x) + 1.f; d.y = __builtin_amdgcn_exp2f(z.y) + 1.f;
;                             f32x2 r; r.x = __builtin_amdgcn_rcpf(d.x); r.y = __builtin_amdgcn_rcpf(d.y);
;                             const f32x2 o = (a * v) * r;
;                             gq[m][n * 2 + ep] = cvt_pk_bf16(o.x, o.y);
	v_pk_fma_f32 v[234:235], v[118:119], v[206:207], v[214:215]
	v_pk_fma_f32 v[236:237], v[102:103], v[206:207], v[214:215]
	v_pk_fma_f32 v[238:239], v[86:87], v[206:207], v[214:215]
	v_pk_fma_f32 v[240:241], v[54:55], v[206:207], v[214:215]
	v_pk_fma_f32 v[236:237], v[118:119], v[202:203], v[236:237]
	v_pk_fma_f32 v[238:239], v[102:103], v[202:203], v[238:239]
	v_pk_fma_f32 v[240:241], v[86:87], v[202:203], v[240:241]
	v_fmac_f32_dpp v234, v54, v202 row_shr:1 row_mask:0xf bank_mask:0xf bound_ctrl:1
	v_fmac_f32_dpp v235, v55, v203 row_shr:1 row_mask:0xf bank_mask:0xf bound_ctrl:1
	v_pk_fma_f32 v[236:237], v[86:87], v[210:211], v[236:237]
	v_pk_fma_f32 v[238:239], v[54:55], v[210:211], v[238:239]
	v_pk_fma_f32 v[234:235], v[102:103], v[210:211], v[234:235]
	v_fmac_f32_dpp v240, v118, v210 row_shl:1 row_mask:0xf bank_mask:0xf bound_ctrl:1
	v_fmac_f32_dpp v241, v119, v211 row_shl:1 row_mask:0xf bank_mask:0xf bound_ctrl:1
	v_cvt_pk_bf16_f32 v185, v234, v235
	v_cvt_pk_bf16_f32 v193, v240, v241
	v_pk_fma_f32 v[242:243], v[126:127], v[208:209], v[216:217]
	v_pk_fma_f32 v[244:245], v[110:111], v[208:209], v[216:217]
	v_pk_fma_f32 v[246:247], v[94:95], v[208:209], v[216:217]
	v_pk_fma_f32 v[248:249], v[70:71], v[208:209], v[216:217]
	v_pk_fma_f32 v[244:245], v[126:127], v[204:205], v[244:245]
	v_pk_fma_f32 v[246:247], v[110:111], v[204:205], v[246:247]
	v_pk_fma_f32 v[248:249], v[94:95], v[204:205], v[248:249]
	v_fmac_f32_dpp v242, v70, v204 row_shr:1 row_mask:0xf bank_mask:0xf bound_ctrl:1
	v_fmac_f32_dpp v243, v71, v205 row_shr:1 row_mask:0xf bank_mask:0xf bound_ctrl:1
	v_pk_fma_f32 v[244:245], v[94:95], v[212:213], v[244:245]
	v_pk_fma_f32 v[246:247], v[70:71], v[212:213], v[246:247]
	v_pk_fma_f32 v[242:243], v[110:111], v[212:213], v[242:243]
	v_fmac_f32_dpp v248, v126, v212 row_shl:1 row_mask:0xf bank_mask:0xf bound_ctrl:1
	v_fmac_f32_dpp v249, v127, v213 row_shl:1 row_mask:0xf bank_mask:0xf bound_ctrl:1
	v_cvt_pk_bf16_f32 v189, v242, v243
	v_cvt_pk_bf16_f32 v155, v248, v249
	ds_read_b64 v[202:203], v132 offset:16
	ds_read_b64 v[204:205], v132 offset:144
	ds_read_b64 v[206:207], v132 offset:272
	ds_read_b64 v[208:209], v132 offset:400
	ds_read_b64 v[210:211], v132 offset:528
	ds_read_b64 v[212:213], v132 offset:656
	ds_read_b64 v[214:215], v132 offset:784
	ds_read_b64 v[216:217], v132 offset:912
	v_pk_mul_f32 v[138:139], v[234:235], v[234:235]
	v_pk_mul_f32 v[140:141], v[236:237], v[236:237]
	v_pk_mul_f32 v[142:143], v[238:239], v[238:239]
	v_pk_mul_f32 v[144:145], v[240:241], v[240:241]
	v_pk_fma_f32 v[138:139], v[138:139], v[134:135], v[136:137]
	v_pk_fma_f32 v[140:141], v[140:141], v[134:135], v[136:137]
	v_pk_fma_f32 v[142:143], v[142:143], v[134:135], v[136:137]
	v_pk_fma_f32 v[144:145], v[144:145], v[134:135], v[136:137]
	v_pk_mul_f32 v[138:139], v[234:235], v[138:139]
	v_pk_mul_f32 v[140:141], v[236:237], v[140:141]
	v_pk_mul_f32 v[142:143], v[238:239], v[142:143]
	v_pk_mul_f32 v[144:145], v[240:241], v[144:145]
	v_exp_f32_e32 v138, v138
	v_exp_f32_e32 v139, v139
	v_exp_f32_e32 v140, v140
	v_exp_f32_e32 v141, v141
	v_exp_f32_e32 v142, v142
	v_exp_f32_e32 v143, v143
	v_exp_f32_e32 v144, v144
	v_exp_f32_e32 v145, v145
	v_pk_mul_f32 v[146:147], v[234:235], v[242:243]
	v_pk_mul_f32 v[148:149], v[236:237], v[244:245]
	v_pk_mul_f32 v[150:151], v[238:239], v[246:247]
	v_pk_mul_f32 v[152:153], v[240:241], v[248:249]
	v_pk_add_f32 v[138:139], v[138:139], 1.0 op_sel_hi:[1,0]
	v_pk_add_f32 v[140:141], v[140:141], 1.0 op_sel_hi:[1,0]
	v_pk_add_f32 v[142:143], v[142:143], 1.0 op_sel_hi:[1,0]
	v_pk_add_f32 v[144:145], v[144:145], 1.0 op_sel_hi:[1,0]
	v_rcp_f32_e32 v138, v138
	v_rcp_f32_e32 v139, v139
	v_rcp_f32_e32 v140, v140
	v_rcp_f32_e32 v141, v141
	v_rcp_f32_e32 v142, v142
	v_rcp_f32_e32 v143, v143
	v_rcp_f32_e32 v144, v144
	v_rcp_f32_e32 v145, v145
	v_pk_mul_f32 v[146:147], v[146:147], v[138:139]
	v_pk_mul_f32 v[148:149], v[148:149], v[140:141]
	v_pk_mul_f32 v[150:151], v[150:151], v[142:143]
	v_pk_mul_f32 v[152:153], v[152:153], v[144:145]
	v_cvt_pk_bf16_f32 v219, v146, v147
	v_cvt_pk_bf16_f32 v223, v148, v149
	v_cvt_pk_bf16_f32 v227, v150, v151
	v_cvt_pk_bf16_f32 v231, v152, v153
	s_waitcnt lgkmcnt(0)
	v_pk_fma_f32 v[234:235], v[112:113], v[206:207], v[214:215]
	v_pk_fma_f32 v[236:237], v[96:97], v[206:207], v[214:215]
	v_pk_fma_f32 v[238:239], v[80:81], v[206:207], v[214:215]
	v_pk_fma_f32 v[240:241], v[48:49], v[206:207], v[214:215]
	v_pk_fma_f32 v[236:237], v[112:113], v[202:203], v[236:237]
	v_pk_fma_f32 v[238:239], v[96:97], v[202:203], v[238:239]
	v_pk_fma_f32 v[240:241], v[80:81], v[202:203], v[240:241]
	v_fmac_f32_dpp v234, v48, v202 row_shr:1 row_mask:0xf bank_mask:0xf bound_ctrl:1
	v_fmac_f32_dpp v235, v49, v203 row_shr:1 row_mask:0xf bank_mask:0xf bound_ctrl:1
	v_pk_fma_f32 v[236:237], v[80:81], v[210:211], v[236:237]
	v_pk_fma_f32 v[238:239], v[48:49], v[210:211], v[238:239]
	v_pk_fma_f32 v[234:235], v[96:97], v[210:211], v[234:235]
	v_fmac_f32_dpp v240, v112, v210 row_shl:1 row_mask:0xf bank_mask:0xf bound_ctrl:1
	v_fmac_f32_dpp v241, v113, v211 row_shl:1 row_mask:0xf bank_mask:0xf bound_ctrl:1
	v_cvt_pk_bf16_f32 v186, v234, v235
	v_cvt_pk_bf16_f32 v194, v240, v241
	v_pk_fma_f32 v[242:243], v[120:121], v[208:209], v[216:217]
	v_pk_fma_f32 v[244:245], v[104:105], v[208:209], v[216:217]
	v_pk_fma_f32 v[246:247], v[88:89], v[208:209], v[216:217]
	v_pk_fma_f32 v[248:249], v[60:61], v[208:209], v[216:217]
	v_pk_fma_f32 v[244:245], v[120:121], v[204:205], v[244:245]
	v_pk_fma_f32 v[246:247], v[104:105], v[204:205], v[246:247]
	v_pk_fma_f32 v[248:249], v[88:89], v[204:205], v[248:249]
	v_fmac_f32_dpp v242, v60, v204 row_shr:1 row_mask:0xf bank_mask:0xf bound_ctrl:1
;     __device__ __forceinline__ void operator()(const f32x4 (&acc)[2][2][4][2], const Unit& u) const {
;     ...
;                     for (int ep = 0; ep < 2; ++ep) {
;                         f32x2 cres[2][4];
; #pragma unroll
;                         for (int part = 0; part < 2; ++part) {
;                             const f32x2 w0 = (f32x2){W[part][0][2 * ep], W[part][0][2 * ep + 1]}, w1 = (f32x2){W[part][1][2 * ep], W[part][1][2 * ep + 1]};
;                             const f32x2 w2 = (f32x2){W[part][2][2 * ep], W[part][2][2 * ep + 1]}, bb = (f32x2){W[part][3][2 * ep], W[part][3][2 * ep + 1]};
;                             const f32x2 w0a = w0 * n0, w0b = w0 * m0, w2a = w2 * n15, w2b = w2 * m15;
;                             f32x2 X[4], R[4], L[4];
; #pragma unroll
;                             for (int m = 0; m < 4; ++m) { X[m] = (f32x2){acc[ai][part][m][n][2 * ep], acc[ai][part][m][n][2 * ep + 1]};
;                                 R[m] = (f32x2){dpp_prev(X[m].x), dpp_prev(X[m].y)}; L[m] = (f32x2){dpp_next(X[m].x), dpp_next(X[m].y)}; }
; #pragma unroll
;                             for (int m = 0; m < 4; ++m) {
;                                 f32x2 c = X[m] * w1 + bb; c = R[m] * w0a + c; c = L[m] * w2a + c;
;                                 if (m > 0) c = R[m > 0 ? m - 1 : 0] * w0b + c;
;                                 if (m < 3) c = L[m < 3 ? m + 1 : 3] * w2b + c;
;                                 cres[part][m] = c;
;                             }
;                             pe[0][part][n * 2 + ep] = cvt_pk_bf16(cres[part][0].x, cres[part][0].y);
;                             pe[1][part][n * 2 + ep] = cvt_pk_bf16(cres[part][3].x, cres[part][3].y);
;                             __builtin_amdgcn_sched_barrier(0);
;                         }
; #pragma unroll
;                         for (int m = 0; m < 4; ++m) {
;                             const f32x2 a = cres[0][m], v = cres[1][m];
;                             const f32x2 t = (a * a) * (-0.10294324f) + (-2.3022082f), z = a * t;
;                             f32x2 d; d.x = __builtin_amdgcn_exp2f(z.x) + 1.f; d.y = __builtin_amdgcn_exp2f(z.y) + 1.f;
;                             f32x2 r; r.x = __builtin_amdgcn_rcpf(d.x); r.y = __builtin_amdgcn_rcpf(d.y);
;                             const f32x2 o = (a * v) * r;
;                             gq[m][n * 2 + ep] = cvt_pk_bf16(o.x, o.y);
	v_fmac_f32_dpp v243, v61, v205 row_shr:1 row_mask:0xf bank_mask:0xf bound_ctrl:1
	v_pk_fma_f32 v[244:245], v[88:89], v[212:213], v[244:245]
	v_pk_fma_f32 v[246:247], v[60:61], v[212:213], v[246:247]
	v_pk_fma_f32 v[242:243], v[104:105], v[212:213], v[242:243]
	v_fmac_f32_dpp v248, v120, v212 row_shl:1 row_mask:0xf bank_mask:0xf bound_ctrl:1
	v_fmac_f32_dpp v249, v121, v213 row_shl:1 row_mask:0xf bank_mask:0xf bound_ctrl:1
	v_cvt_pk_bf16_f32 v190, v242, v243
	v_cvt_pk_bf16_f32 v156, v248, v249
	ds_read_b64 v[202:203], v132 offset:24
	ds_read_b64 v[204:205], v132 offset:152
	ds_read_b64 v[206:207], v132 offset:280
	ds_read_b64 v[208:209], v132 offset:408
	ds_read_b64 v[210:211], v132 offset:536
	ds_read_b64 v[212:213], v132 offset:664
	ds_read_b64 v[214:215], v132 offset:792
	ds_read_b64 v[216:217], v132 offset:920
	v_pk_mul_f32 v[138:139], v[234:235], v[234:235]
	v_pk_mul_f32 v[140:141], v[236:237], v[236:237]
	v_pk_mul_f32 v[142:143], v[238:239], v[238:239]
	v_pk_mul_f32 v[144:145], v[240:241], v[240:241]
	v_pk_fma_f32 v[138:139], v[138:139], v[134:135], v[136:137]
	v_pk_fma_f32 v[140:141], v[140:141], v[134:135], v[136:137]
	v_pk_fma_f32 v[142:143], v[142:143], v[134:135], v[136:137]
	v_pk_fma_f32 v[144:145], v[144:145], v[134:135], v[136:137]
	v_pk_mul_f32 v[138:139], v[234:235], v[138:139]
	v_pk_mul_f32 v[140:141], v[236:237], v[140:141]
	v_pk_mul_f32 v[142:143], v[238:239], v[142:143]
	v_pk_mul_f32 v[144:145], v[240:241], v[144:145]
	v_exp_f32_e32 v138, v138
	v_exp_f32_e32 v139, v139
	v_exp_f32_e32 v140, v140
	v_exp_f32_e32 v141, v141
	v_exp_f32_e32 v142, v142
	v_exp_f32_e32 v143, v143
	v_exp_f32_e32 v144, v144
	v_exp_f32_e32 v145, v145
	v_pk_mul_f32 v[146:147], v[234:235], v[242:243]
	v_pk_mul_f32 v[148:149], v[236:237], v[244:245]
	v_pk_mul_f32 v[150:151], v[238:239], v[246:247]
	v_pk_mul_f32 v[152:153], v[240:241], v[248:249]
	v_pk_add_f32 v[138:139], v[138:139], 1.0 op_sel_hi:[1,0]
	v_pk_add_f32 v[140:141], v[140:141], 1.0 op_sel_hi:[1,0]
	v_pk_add_f32 v[142:143], v[142:143], 1.0 op_sel_hi:[1,0]
	v_pk_add_f32 v[144:145], v[144:145], 1.0 op_sel_hi:[1,0]
	v_rcp_f32_e32 v138, v138
	v_rcp_f32_e32 v139, v139
	v_rcp_f32_e32 v140, v140
	v_rcp_f32_e32 v141, v141
	v_rcp_f32_e32 v142, v142
	v_rcp_f32_e32 v143, v143
	v_rcp_f32_e32 v144, v144
	v_rcp_f32_e32 v145, v145
	v_pk_mul_f32 v[146:147], v[146:147], v[138:139]
	v_pk_mul_f32 v[148:149], v[148:149], v[140:141]
	v_pk_mul_f32 v[150:151], v[150:151], v[142:143]
	v_pk_mul_f32 v[152:153], v[152:153], v[144:145]
	v_cvt_pk_bf16_f32 v220, v146, v147
	v_cvt_pk_bf16_f32 v224, v148, v149
	v_cvt_pk_bf16_f32 v228, v150, v151
	v_cvt_pk_bf16_f32 v232, v152, v153
	s_waitcnt lgkmcnt(0)
	v_pk_fma_f32 v[234:235], v[114:115], v[206:207], v[214:215]
	v_pk_fma_f32 v[236:237], v[98:99], v[206:207], v[214:215]
	v_pk_fma_f32 v[238:239], v[82:83], v[206:207], v[214:215]
	v_pk_fma_f32 v[240:241], v[50:51], v[206:207], v[214:215]
	v_pk_fma_f32 v[236:237], v[114:115], v[202:203], v[236:237]
	v_pk_fma_f32 v[238:239], v[98:99], v[202:203], v[238:239]
	v_pk_fma_f32 v[240:241], v[82:83], v[202:203], v[240:241]
	v_fmac_f32_dpp v234, v50, v202 row_shr:1 row_mask:0xf bank_mask:0xf bound_ctrl:1
	v_fmac_f32_dpp v235, v51, v203 row_shr:1 row_mask:0xf bank_mask:0xf bound_ctrl:1
	v_pk_fma_f32 v[236:237], v[82:83], v[210:211], v[236:237]
	v_pk_fma_f32 v[238:239], v[50:51], v[210:211], v[238:239]
	v_pk_fma_f32 v[234:235], v[98:99], v[210:211], v[234:235]
	v_fmac_f32_dpp v240, v114, v210 row_shl:1 row_mask:0xf bank_mask:0xf bound_ctrl:1
	v_fmac_f32_dpp v241, v115, v211 row_shl:1 row_mask:0xf bank_mask:0xf bound_ctrl:1
	v_cvt_pk_bf16_f32 v187, v234, v235
	v_cvt_pk_bf16_f32 v195, v240, v241
	v_pk_fma_f32 v[242:243], v[122:123], v[208:209], v[216:217]
	v_pk_fma_f32 v[244:245], v[106:107], v[208:209], v[216:217]
	v_pk_fma_f32 v[246:247], v[90:91], v[208:209], v[216:217]
	v_pk_fma_f32 v[248:249], v[62:63], v[208:209], v[216:217]
	v_pk_fma_f32 v[244:245], v[122:123], v[204:205], v[244:245]
	v_pk_fma_f32 v[246:247], v[106:107], v[204:205], v[246:247]
	v_pk_fma_f32 v[248:249], v[90:91], v[204:205], v[248:249]
	v_fmac_f32_dpp v242, v62, v204 row_shr:1 row_mask:0xf bank_mask:0xf bound_ctrl:1
	v_fmac_f32_dpp v243, v63, v205 row_shr:1 row_mask:0xf bank_mask:0xf bound_ctrl:1
	v_pk_fma_f32 v[244:245], v[90:91], v[212:213], v[244:245]
	v_pk_fma_f32 v[246:247], v[62:63], v[212:213], v[246:247]
	v_pk_fma_f32 v[242:243], v[106:107], v[212:213], v[242:243]
	v_fmac_f32_dpp v248, v122, v212 row_shl:1 row_mask:0xf bank_mask:0xf bound_ctrl:1
	v_fmac_f32_dpp v249, v123, v213 row_shl:1 row_mask:0xf bank_mask:0xf bound_ctrl:1
	v_cvt_pk_bf16_f32 v191, v242, v243
	v_cvt_pk_bf16_f32 v157, v248, v249
	ds_read_b64 v[202:203], v132 offset:0
	ds_read_b64 v[204:205], v132 offset:128
	ds_read_b64 v[206:207], v132 offset:256
	ds_read_b64 v[208:209], v132 offset:384
	ds_read_b64 v[210:211], v132 offset:512
	ds_read_b64 v[212:213], v132 offset:640
	ds_read_b64 v[214:215], v132 offset:768
	ds_read_b64 v[216:217], v132 offset:896
	v_pk_mul_f32 v[138:139], v[234:235], v[234:235]
	v_pk_mul_f32 v[140:141], v[236:237], v[236:237]
	v_pk_mul_f32 v[142:143], v[238:239], v[238:239]
	v_pk_mul_f32 v[144:145], v[240:241], v[240:241]
	v_pk_fma_f32 v[138:139], v[138:139], v[134:135], v[136:137]
	v_pk_fma_f32 v[140:141], v[140:141], v[134:135], v[136:137]
	v_pk_fma_f32 v[142:143], v[142:143], v[134:135], v[136:137]
	v_pk_fma_f32 v[144:145], v[144:145], v[134:135], v[136:137]
	v_pk_mul_f32 v[138:139], v[234:235], v[138:139]
	v_pk_mul_f32 v[140:141], v[236:237], v[140:141]
	v_pk_mul_f32 v[142:143], v[238:239], v[142:143]
	v_pk_mul_f32 v[144:145], v[240:241], v[144:145]
;     __device__ __forceinline__ void operator()(const f32x4 (&acc)[2][2][4][2], const Unit& u) const {
;     ...
;                     for (int ep = 0; ep < 2; ++ep) {
;                         f32x2 cres[2][4];
; #pragma unroll
;                         for (int part = 0; part < 2; ++part) {
;                             const f32x2 w0 = (f32x2){W[part][0][2 * ep], W[part][0][2 * ep + 1]}, w1 = (f32x2){W[part][1][2 * ep], W[part][1][2 * ep + 1]};
;                             const f32x2 w2 = (f32x2){W[part][2][2 * ep], W[part][2][2 * ep + 1]}, bb = (f32x2){W[part][3][2 * ep], W[part][3][2 * ep + 1]};
;                             const f32x2 w0a = w0 * n0, w0b = w0 * m0, w2a = w2 * n15, w2b = w2 * m15;
;                             f32x2 X[4], R[4], L[4];
; #pragma unroll
;                             for (int m = 0; m < 4; ++m) { X[m] = (f32x2){acc[ai][part][m][n][2 * ep], acc[ai][part][m][n][2 * ep + 1]};
;                                 R[m] = (f32x2){dpp_prev(X[m].x), dpp_prev(X[m].y)}; L[m] = (f32x2){dpp_next(X[m].x), dpp_next(X[m].y)}; }
; #pragma unroll
;                             for (int m = 0; m < 4; ++m) {
;                                 f32x2 c = X[m] * w1 + bb; c = R[m] * w0a + c; c = L[m] * w2a + c;
;                                 if (m > 0) c = R[m > 0 ? m - 1 : 0] * w0b + c;
;                                 if (m < 3) c = L[m < 3 ? m + 1 : 3] * w2b + c;
;                                 cres[part][m] = c;
;                             }
;                             pe[0][part][n * 2 + ep] = cvt_pk_bf16(cres[part][0].x, cres[part][0].y);
;                             pe[1][part][n * 2 + ep] = cvt_pk_bf16(cres[part][3].x, cres[part][3].y);
;                             __builtin_amdgcn_sched_barrier(0);
;                         }
; #pragma unroll
;                         for (int m = 0; m < 4; ++m) {
;                             const f32x2 a = cres[0][m], v = cres[1][m];
;                             const f32x2 t = (a * a) * (-0.10294324f) + (-2.3022082f), z = a * t;
;                             f32x2 d; d.x = __builtin_amdgcn_exp2f(z.x) + 1.f; d.y = __builtin_amdgcn_exp2f(z.y) + 1.f;
;                             f32x2 r; r.x = __builtin_amdgcn_rcpf(d.x); r.y = __builtin_amdgcn_rcpf(d.y);
;                             const f32x2 o = (a * v) * r;
;                             gq[m][n * 2 + ep] = cvt_pk_bf16(o.x, o.y);
	v_exp_f32_e32 v138, v138
	v_exp_f32_e32 v139, v139
	v_exp_f32_e32 v140, v140
	v_exp_f32_e32 v141, v141
	v_exp_f32_e32 v142, v142
	v_exp_f32_e32 v143, v143
	v_exp_f32_e32 v144, v144
	v_exp_f32_e32 v145, v145
	v_pk_mul_f32 v[146:147], v[234:235], v[242:243]
	v_pk_mul_f32 v[148:149], v[236:237], v[244:245]
	v_pk_mul_f32 v[150:151], v[238:239], v[246:247]
	v_pk_mul_f32 v[152:153], v[240:241], v[248:249]
	v_pk_add_f32 v[138:139], v[138:139], 1.0 op_sel_hi:[1,0]
	v_pk_add_f32 v[140:141], v[140:141], 1.0 op_sel_hi:[1,0]
	v_pk_add_f32 v[142:143], v[142:143], 1.0 op_sel_hi:[1,0]
	v_pk_add_f32 v[144:145], v[144:145], 1.0 op_sel_hi:[1,0]
	v_rcp_f32_e32 v138, v138
	v_rcp_f32_e32 v139, v139
	v_rcp_f32_e32 v140, v140
	v_rcp_f32_e32 v141, v141
	v_rcp_f32_e32 v142, v142
	v_rcp_f32_e32 v143, v143
	v_rcp_f32_e32 v144, v144
	v_rcp_f32_e32 v145, v145
	v_pk_mul_f32 v[146:147], v[146:147], v[138:139]
	v_pk_mul_f32 v[148:149], v[148:149], v[140:141]
	v_pk_mul_f32 v[150:151], v[150:151], v[142:143]
	v_pk_mul_f32 v[152:153], v[152:153], v[144:145]
	v_cvt_pk_bf16_f32 v221, v146, v147
	v_cvt_pk_bf16_f32 v225, v148, v149
	v_cvt_pk_bf16_f32 v229, v150, v151
	v_cvt_pk_bf16_f32 v233, v152, v153
	s_mov_b64 s[22:23], exec
	s_mov_b64 exec, s[6:7]
	v_cvt_pk_bf16_f32 v138, v116, v117
	v_cvt_pk_bf16_f32 v139, v118, v119
	v_cvt_pk_bf16_f32 v140, v112, v113
	v_cvt_pk_bf16_f32 v141, v114, v115
	v_cvt_pk_bf16_f32 v142, v124, v125
	v_cvt_pk_bf16_f32 v143, v126, v127
	v_cvt_pk_bf16_f32 v144, v120, v121
	v_cvt_pk_bf16_f32 v145, v122, v123
	global_store_dwordx4 v129, v[138:141], s[10:11]
	global_store_dwordx4 v129, v[142:145], s[10:11] offset:16
	global_store_dwordx4 v129, v[184:187], s[10:11] offset:32
	global_store_dwordx4 v129, v[188:191], s[10:11] offset:48
	s_mov_b64 exec, s[8:9]
	v_cvt_pk_bf16_f32 v146, v52, v53
	v_cvt_pk_bf16_f32 v147, v54, v55
	v_cvt_pk_bf16_f32 v148, v48, v49
	v_cvt_pk_bf16_f32 v149, v50, v51
	v_cvt_pk_bf16_f32 v150, v68, v69
	v_cvt_pk_bf16_f32 v151, v70, v71
	v_cvt_pk_bf16_f32 v152, v60, v61
	v_cvt_pk_bf16_f32 v153, v62, v63
	global_store_dwordx4 v162, v[146:149], s[10:11]
	global_store_dwordx4 v162, v[150:153], s[10:11] offset:16
	global_store_dwordx4 v162, v[192:195], s[10:11] offset:32
	global_store_dwordx4 v162, v[154:157], s[10:11] offset:48
	s_mov_b64 exec, s[56:57]
	global_store_dwordx4 v128, v[218:221], s[52:53]
	s_mov_b64 exec, s[22:23]
	v_add_u32_e32 v133, 0x1600, v128
	v_add_u32_e32 v130, 0x2c00, v128
	v_add_u32_e32 v131, 0x4200, v128
	global_store_dwordx4 v133, v[222:225], s[52:53]
	global_store_dwordx4 v130, v[226:229], s[52:53]
	s_mov_b64 exec, s[58:59]
	global_store_dwordx4 v131, v[230:233], s[52:53]
	s_mov_b64 exec, s[22:23]
	v_add_u32_e32 v128, 0xb0000, v128
	v_add_u32_e32 v129, 0x16000, v129
	v_add_u32_e32 v162, 0x16000, v162
	s_nop 1
	s_waitcnt lgkmcnt(0)
	v_pk_fma_f32 v[234:235], v[64:65], v[206:207], v[214:215]
	v_pk_fma_f32 v[236:237], v[36:37], v[206:207], v[214:215]
	v_pk_fma_f32 v[238:239], v[20:21], v[206:207], v[214:215]
	v_pk_fma_f32 v[240:241], v[4:5], v[206:207], v[214:215]
	v_pk_fma_f32 v[236:237], v[64:65], v[202:203], v[236:237]
	v_pk_fma_f32 v[238:239], v[36:37], v[202:203], v[238:239]
	v_pk_fma_f32 v[240:241], v[20:21], v[202:203], v[240:241]
	v_fmac_f32_dpp v234, v4, v202 row_shr:1 row_mask:0xf bank_mask:0xf bound_ctrl:1
	v_fmac_f32_dpp v235, v5, v203 row_shr:1 row_mask:0xf bank_mask:0xf bound_ctrl:1
	v_pk_fma_f32 v[236:237], v[20:21], v[210:211], v[236:237]
	v_pk_fma_f32 v[238:239], v[4:5], v[210:211], v[238:239]
	v_pk_fma_f32 v[234:235], v[36:37], v[210:211], v[234:235]
	v_fmac_f32_dpp v240, v64, v210 row_shl:1 row_mask:0xf bank_mask:0xf bound_ctrl:1
	v_fmac_f32_dpp v241, v65, v211 row_shl:1 row_mask:0xf bank_mask:0xf bound_ctrl:1
	v_cvt_pk_bf16_f32 v184, v234, v235
	v_cvt_pk_bf16_f32 v192, v240, v241
	v_pk_fma_f32 v[242:243], v[76:77], v[208:209], v[216:217]
	v_pk_fma_f32 v[244:245], v[44:45], v[208:209], v[216:217]
	v_pk_fma_f32 v[246:247], v[28:29], v[208:209], v[216:217]
	v_pk_fma_f32 v[248:249], v[12:13], v[208:209], v[216:217]
	v_pk_fma_f32 v[244:245], v[76:77], v[204:205], v[244:245]
	v_pk_fma_f32 v[246:247], v[44:45], v[204:205], v[246:247]
	v_pk_fma_f32 v[248:249], v[28:29], v[204:205], v[248:249]
	v_fmac_f32_dpp v242, v12, v204 row_shr:1 row_mask:0xf bank_mask:0xf bound_ctrl:1
	v_fmac_f32_dpp v243, v13, v205 row_shr:1 row_mask:0xf bank_mask:0xf bound_ctrl:1
	v_pk_fma_f32 v[244:245], v[28:29], v[212:213], v[244:245]
	v_pk_fma_f32 v[246:247], v[12:13], v[212:213], v[246:247]
	v_pk_fma_f32 v[242:243], v[44:45], v[212:213], v[242:243]
	v_fmac_f32_dpp v248, v76, v212 row_shl:1 row_mask:0xf bank_mask:0xf bound_ctrl:1
	v_fmac_f32_dpp v249, v77, v213 row_shl:1 row_mask:0xf bank_mask:0xf bound_ctrl:1
	v_cvt_pk_bf16_f32 v188, v242, v243
	v_cvt_pk_bf16_f32 v154, v248, v249
	ds_read_b64 v[202:203], v132 offset:8
	ds_read_b64 v[204:205], v132 offset:136
	ds_read_b64 v[206:207], v132 offset:264
	ds_read_b64 v[208:209], v132 offset:392
	ds_read_b64 v[210:211], v132 offset:520
	ds_read_b64 v[212:213], v132 offset:648
	ds_read_b64 v[214:215], v132 offset:776
	ds_read_b64 v[216:217], v132 offset:904
	v_pk_mul_f32 v[138:139], v[234:235], v[234:235]
	v_pk_mul_f32 v[140:141], v[236:237], v[236:237]
	v_pk_mul_f32 v[142:143], v[238:239], v[238:239]
	v_pk_mul_f32 v[144:145], v[240:241], v[240:241]
	v_pk_fma_f32 v[138:139], v[138:139], v[134:135], v[136:137]
	v_pk_fma_f32 v[140:141], v[140:141], v[134:135], v[136:137]
	v_pk_fma_f32 v[142:143], v[142:143], v[134:135], v[136:137]
	v_pk_fma_f32 v[144:145], v[144:145], v[134:135], v[136:137]
	v_pk_mul_f32 v[138:139], v[234:235], v[138:139]
	v_pk_mul_f32 v[140:141], v[236:237], v[140:141]
	v_pk_mul_f32 v[142:143], v[238:239], v[142:143]
	v_pk_mul_f32 v[144:145], v[240:241], v[144:145]
	v_exp_f32_e32 v138, v138
	v_exp_f32_e32 v139, v139
	v_exp_f32_e32 v140, v140
	v_exp_f32_e32 v141, v141
	v_exp_f32_e32 v142, v142
	v_exp_f32_e32 v143, v143
	v_exp_f32_e32 v144, v144
	v_exp_f32_e32 v145, v145
	v_pk_mul_f32 v[146:147], v[234:235], v[242:243]
	v_pk_mul_f32 v[148:149], v[236:237], v[244:245]
	v_pk_mul_f32 v[150:151], v[238:239], v[246:247]
	v_pk_mul_f32 v[152:153], v[240:241], v[248:249]
	v_pk_add_f32 v[138:139], v[138:139], 1.0 op_sel_hi:[1,0]
	v_pk_add_f32 v[140:141], v[140:141], 1.0 op_sel_hi:[1,0]
	v_pk_add_f32 v[142:143], v[142:143], 1.0 op_sel_hi:[1,0]
	v_pk_add_f32 v[144:145], v[144:145], 1.0 op_sel_hi:[1,0]
	v_rcp_f32_e32 v138, v138
	v_rcp_f32_e32 v139, v139
	v_rcp_f32_e32 v140, v140
	v_rcp_f32_e32 v141, v141
	v_rcp_f32_e32 v142, v142
	v_rcp_f32_e32 v143, v143
	v_rcp_f32_e32 v144, v144
	v_rcp_f32_e32 v145, v145
	v_pk_mul_f32 v[146:147], v[146:147], v[138:139]
	v_pk_mul_f32 v[148:149], v[148:149], v[140:141]
	v_pk_mul_f32 v[150:151], v[150:151], v[142:143]
	v_pk_mul_f32 v[152:153], v[152:153], v[144:145]
	v_cvt_pk_bf16_f32 v218, v146, v147
	v_cvt_pk_bf16_f32 v222, v148, v149
	v_cvt_pk_bf16_f32 v226, v150, v151
	v_cvt_pk_bf16_f32 v230, v152, v153
	s_waitcnt lgkmcnt(0)
;     __device__ __forceinline__ void operator()(const f32x4 (&acc)[2][2][4][2], const Unit& u) const {
;     ...
;                     for (int ep = 0; ep < 2; ++ep) {
;                         f32x2 cres[2][4];
; #pragma unroll
;                         for (int part = 0; part < 2; ++part) {
;                             const f32x2 w0 = (f32x2){W[part][0][2 * ep], W[part][0][2 * ep + 1]}, w1 = (f32x2){W[part][1][2 * ep], W[part][1][2 * ep + 1]};
;                             const f32x2 w2 = (f32x2){W[part][2][2 * ep], W[part][2][2 * ep + 1]}, bb = (f32x2){W[part][3][2 * ep], W[part][3][2 * ep + 1]};
;                             const f32x2 w0a = w0 * n0, w0b = w0 * m0, w2a = w2 * n15, w2b = w2 * m15;
;                             f32x2 X[4], R[4], L[4];
; #pragma unroll
;                             for (int m = 0; m < 4; ++m) { X[m] = (f32x2){acc[ai][part][m][n][2 * ep], acc[ai][part][m][n][2 * ep + 1]};
;                                 R[m] = (f32x2){dpp_prev(X[m].x), dpp_prev(X[m].y)}; L[m] = (f32x2){dpp_next(X[m].x), dpp_next(X[m].y)}; }
; #pragma unroll
;                             for (int m = 0; m < 4; ++m) {
;                                 f32x2 c = X[m] * w1 + bb; c = R[m] * w0a + c; c = L[m] * w2a + c;
;                                 if (m > 0) c = R[m > 0 ? m - 1 : 0] * w0b + c;
;                                 if (m < 3) c = L[m < 3 ? m + 1 : 3] * w2b + c;
;                                 cres[part][m] = c;
;                             }
;                             pe[0][part][n * 2 + ep] = cvt_pk_bf16(cres[part][0].x, cres[part][0].y);
;                             pe[1][part][n * 2 + ep] = cvt_pk_bf16(cres[part][3].x, cres[part][3].y);
;                             __builtin_amdgcn_sched_barrier(0);
;                         }
; #pragma unroll
;                         for (int m = 0; m < 4; ++m) {
;                             const f32x2 a = cres[0][m], v = cres[1][m];
;                             const f32x2 t = (a * a) * (-0.10294324f) + (-2.3022082f), z = a * t;
;                             f32x2 d; d.x = __builtin_amdgcn_exp2f(z.x) + 1.f; d.y = __builtin_amdgcn_exp2f(z.y) + 1.f;
;                             f32x2 r; r.x = __builtin_amdgcn_rcpf(d.x); r.y = __builtin_amdgcn_rcpf(d.y);
;                             const f32x2 o = (a * v) * r;
;                             gq[m][n * 2 + ep] = cvt_pk_bf16(o.x, o.y);
	v_pk_fma_f32 v[234:235], v[66:67], v[206:207], v[214:215]
	v_pk_fma_f32 v[236:237], v[38:39], v[206:207], v[214:215]
	v_pk_fma_f32 v[238:239], v[22:23], v[206:207], v[214:215]
	v_pk_fma_f32 v[240:241], v[6:7], v[206:207], v[214:215]
	v_pk_fma_f32 v[236:237], v[66:67], v[202:203], v[236:237]
	v_pk_fma_f32 v[238:239], v[38:39], v[202:203], v[238:239]
	v_pk_fma_f32 v[240:241], v[22:23], v[202:203], v[240:241]
	v_fmac_f32_dpp v234, v6, v202 row_shr:1 row_mask:0xf bank_mask:0xf bound_ctrl:1
	v_fmac_f32_dpp v235, v7, v203 row_shr:1 row_mask:0xf bank_mask:0xf bound_ctrl:1
	v_pk_fma_f32 v[236:237], v[22:23], v[210:211], v[236:237]
	v_pk_fma_f32 v[238:239], v[6:7], v[210:211], v[238:239]
	v_pk_fma_f32 v[234:235], v[38:39], v[210:211], v[234:235]
	v_fmac_f32_dpp v240, v66, v210 row_shl:1 row_mask:0xf bank_mask:0xf bound_ctrl:1
	v_fmac_f32_dpp v241, v67, v211 row_shl:1 row_mask:0xf bank_mask:0xf bound_ctrl:1
	v_cvt_pk_bf16_f32 v185, v234, v235
	v_cvt_pk_bf16_f32 v193, v240, v241
	v_pk_fma_f32 v[242:243], v[78:79], v[208:209], v[216:217]
	v_pk_fma_f32 v[244:245], v[46:47], v[208:209], v[216:217]
	v_pk_fma_f32 v[246:247], v[30:31], v[208:209], v[216:217]
	v_pk_fma_f32 v[248:249], v[14:15], v[208:209], v[216:217]
	v_pk_fma_f32 v[244:245], v[78:79], v[204:205], v[244:245]
	v_pk_fma_f32 v[246:247], v[46:47], v[204:205], v[246:247]
	v_pk_fma_f32 v[248:249], v[30:31], v[204:205], v[248:249]
	v_fmac_f32_dpp v242, v14, v204 row_shr:1 row_mask:0xf bank_mask:0xf bound_ctrl:1
	v_fmac_f32_dpp v243, v15, v205 row_shr:1 row_mask:0xf bank_mask:0xf bound_ctrl:1
	v_pk_fma_f32 v[244:245], v[30:31], v[212:213], v[244:245]
	v_pk_fma_f32 v[246:247], v[14:15], v[212:213], v[246:247]
	v_pk_fma_f32 v[242:243], v[46:47], v[212:213], v[242:243]
	v_fmac_f32_dpp v248, v78, v212 row_shl:1 row_mask:0xf bank_mask:0xf bound_ctrl:1
	v_fmac_f32_dpp v249, v79, v213 row_shl:1 row_mask:0xf bank_mask:0xf bound_ctrl:1
	v_cvt_pk_bf16_f32 v189, v242, v243
	v_cvt_pk_bf16_f32 v155, v248, v249
	ds_read_b64 v[202:203], v132 offset:16
	ds_read_b64 v[204:205], v132 offset:144
	ds_read_b64 v[206:207], v132 offset:272
	ds_read_b64 v[208:209], v132 offset:400
	ds_read_b64 v[210:211], v132 offset:528
	ds_read_b64 v[212:213], v132 offset:656
	ds_read_b64 v[214:215], v132 offset:784
	ds_read_b64 v[216:217], v132 offset:912
	v_pk_mul_f32 v[138:139], v[234:235], v[234:235]
	v_pk_mul_f32 v[140:141], v[236:237], v[236:237]
	v_pk_mul_f32 v[142:143], v[238:239], v[238:239]
	v_pk_mul_f32 v[144:145], v[240:241], v[240:241]
	v_pk_fma_f32 v[138:139], v[138:139], v[134:135], v[136:137]
	v_pk_fma_f32 v[140:141], v[140:141], v[134:135], v[136:137]
	v_pk_fma_f32 v[142:143], v[142:143], v[134:135], v[136:137]
	v_pk_fma_f32 v[144:145], v[144:145], v[134:135], v[136:137]
	v_pk_mul_f32 v[138:139], v[234:235], v[138:139]
	v_pk_mul_f32 v[140:141], v[236:237], v[140:141]
	v_pk_mul_f32 v[142:143], v[238:239], v[142:143]
	v_pk_mul_f32 v[144:145], v[240:241], v[144:145]
	v_exp_f32_e32 v138, v138
	v_exp_f32_e32 v139, v139
	v_exp_f32_e32 v140, v140
	v_exp_f32_e32 v141, v141
	v_exp_f32_e32 v142, v142
	v_exp_f32_e32 v143, v143
	v_exp_f32_e32 v144, v144
	v_exp_f32_e32 v145, v145
	v_pk_mul_f32 v[146:147], v[234:235], v[242:243]
	v_pk_mul_f32 v[148:149], v[236:237], v[244:245]
	v_pk_mul_f32 v[150:151], v[238:239], v[246:247]
	v_pk_mul_f32 v[152:153], v[240:241], v[248:249]
	v_pk_add_f32 v[138:139], v[138:139], 1.0 op_sel_hi:[1,0]
	v_pk_add_f32 v[140:141], v[140:141], 1.0 op_sel_hi:[1,0]
	v_pk_add_f32 v[142:143], v[142:143], 1.0 op_sel_hi:[1,0]
	v_pk_add_f32 v[144:145], v[144:145], 1.0 op_sel_hi:[1,0]
	v_rcp_f32_e32 v138, v138
	v_rcp_f32_e32 v139, v139
	v_rcp_f32_e32 v140, v140
	v_rcp_f32_e32 v141, v141
	v_rcp_f32_e32 v142, v142
	v_rcp_f32_e32 v143, v143
	v_rcp_f32_e32 v144, v144
	v_rcp_f32_e32 v145, v145
	v_pk_mul_f32 v[146:147], v[146:147], v[138:139]
	v_pk_mul_f32 v[148:149], v[148:149], v[140:141]
	v_pk_mul_f32 v[150:151], v[150:151], v[142:143]
	v_pk_mul_f32 v[152:153], v[152:153], v[144:145]
	v_cvt_pk_bf16_f32 v219, v146, v147
	v_cvt_pk_bf16_f32 v223, v148, v149
	v_cvt_pk_bf16_f32 v227, v150, v151
	v_cvt_pk_bf16_f32 v231, v152, v153
	s_waitcnt lgkmcnt(0)
	v_pk_fma_f32 v[234:235], v[56:57], v[206:207], v[214:215]
	v_pk_fma_f32 v[236:237], v[32:33], v[206:207], v[214:215]
	v_pk_fma_f32 v[238:239], v[16:17], v[206:207], v[214:215]
	v_pk_fma_f32 v[240:241], v[0:1], v[206:207], v[214:215]
	v_pk_fma_f32 v[236:237], v[56:57], v[202:203], v[236:237]
	v_pk_fma_f32 v[238:239], v[32:33], v[202:203], v[238:239]
	v_pk_fma_f32 v[240:241], v[16:17], v[202:203], v[240:241]
	v_fmac_f32_dpp v234, v0, v202 row_shr:1 row_mask:0xf bank_mask:0xf bound_ctrl:1
	v_fmac_f32_dpp v235, v1, v203 row_shr:1 row_mask:0xf bank_mask:0xf bound_ctrl:1
	v_pk_fma_f32 v[236:237], v[16:17], v[210:211], v[236:237]
	v_pk_fma_f32 v[238:239], v[0:1], v[210:211], v[238:239]
	v_pk_fma_f32 v[234:235], v[32:33], v[210:211], v[234:235]
	v_fmac_f32_dpp v240, v56, v210 row_shl:1 row_mask:0xf bank_mask:0xf bound_ctrl:1
	v_fmac_f32_dpp v241, v57, v211 row_shl:1 row_mask:0xf bank_mask:0xf bound_ctrl:1
	v_cvt_pk_bf16_f32 v186, v234, v235
	v_cvt_pk_bf16_f32 v194, v240, v241
	v_pk_fma_f32 v[242:243], v[72:73], v[208:209], v[216:217]
	v_pk_fma_f32 v[244:245], v[40:41], v[208:209], v[216:217]
	v_pk_fma_f32 v[246:247], v[24:25], v[208:209], v[216:217]
	v_pk_fma_f32 v[248:249], v[8:9], v[208:209], v[216:217]
	v_pk_fma_f32 v[244:245], v[72:73], v[204:205], v[244:245]
	v_pk_fma_f32 v[246:247], v[40:41], v[204:205], v[246:247]
	v_pk_fma_f32 v[248:249], v[24:25], v[204:205], v[248:249]
	v_fmac_f32_dpp v242, v8, v204 row_shr:1 row_mask:0xf bank_mask:0xf bound_ctrl:1
;     __device__ __forceinline__ void operator()(const f32x4 (&acc)[2][2][4][2], const Unit& u) const {
;     ...
;                     for (int ep = 0; ep < 2; ++ep) {
;                         f32x2 cres[2][4];
; #pragma unroll
;                         for (int part = 0; part < 2; ++part) {
;                             const f32x2 w0 = (f32x2){W[part][0][2 * ep], W[part][0][2 * ep + 1]}, w1 = (f32x2){W[part][1][2 * ep], W[part][1][2 * ep + 1]};
;                             const f32x2 w2 = (f32x2){W[part][2][2 * ep], W[part][2][2 * ep + 1]}, bb = (f32x2){W[part][3][2 * ep], W[part][3][2 * ep + 1]};
;                             const f32x2 w0a = w0 * n0, w0b = w0 * m0, w2a = w2 * n15, w2b = w2 * m15;
;                             f32x2 X[4], R[4], L[4];
; #pragma unroll
;                             for (int m = 0; m < 4; ++m) { X[m] = (f32x2){acc[ai][part][m][n][2 * ep], acc[ai][part][m][n][2 * ep + 1]};
;                                 R[m] = (f32x2){dpp_prev(X[m].x), dpp_prev(X[m].y)}; L[m] = (f32x2){dpp_next(X[m].x), dpp_next(X[m].y)}; }
; #pragma unroll
;                             for (int m = 0; m < 4; ++m) {
;                                 f32x2 c = X[m] * w1 + bb; c = R[m] * w0a + c; c = L[m] * w2a + c;
;                                 if (m > 0) c = R[m > 0 ? m - 1 : 0] * w0b + c;
;                                 if (m < 3) c = L[m < 3 ? m + 1 : 3] * w2b + c;
;                                 cres[part][m] = c;
;                             }
;                             pe[0][part][n * 2 + ep] = cvt_pk_bf16(cres[part][0].x, cres[part][0].y);
;                             pe[1][part][n * 2 + ep] = cvt_pk_bf16(cres[part][3].x, cres[part][3].y);
;                             __builtin_amdgcn_sched_barrier(0);
;                         }
; #pragma unroll
;                         for (int m = 0; m < 4; ++m) {
;                             const f32x2 a = cres[0][m], v = cres[1][m];
;                             const f32x2 t = (a * a) * (-0.10294324f) + (-2.3022082f), z = a * t;
;                             f32x2 d; d.x = __builtin_amdgcn_exp2f(z.x) + 1.f; d.y = __builtin_amdgcn_exp2f(z.y) + 1.f;
;                             f32x2 r; r.x = __builtin_amdgcn_rcpf(d.x); r.y = __builtin_amdgcn_rcpf(d.y);
;                             const f32x2 o = (a * v) * r;
;                             gq[m][n * 2 + ep] = cvt_pk_bf16(o.x, o.y);
	v_fmac_f32_dpp v243, v9, v205 row_shr:1 row_mask:0xf bank_mask:0xf bound_ctrl:1
	v_pk_fma_f32 v[244:245], v[24:25], v[212:213], v[244:245]
	v_pk_fma_f32 v[246:247], v[8:9], v[212:213], v[246:247]
	v_pk_fma_f32 v[242:243], v[40:41], v[212:213], v[242:243]
	v_fmac_f32_dpp v248, v72, v212 row_shl:1 row_mask:0xf bank_mask:0xf bound_ctrl:1
	v_fmac_f32_dpp v249, v73, v213 row_shl:1 row_mask:0xf bank_mask:0xf bound_ctrl:1
	v_cvt_pk_bf16_f32 v190, v242, v243
	v_cvt_pk_bf16_f32 v156, v248, v249
	ds_read_b64 v[202:203], v132 offset:24
	ds_read_b64 v[204:205], v132 offset:152
	ds_read_b64 v[206:207], v132 offset:280
	ds_read_b64 v[208:209], v132 offset:408
	ds_read_b64 v[210:211], v132 offset:536
	ds_read_b64 v[212:213], v132 offset:664
	ds_read_b64 v[214:215], v132 offset:792
	ds_read_b64 v[216:217], v132 offset:920
	v_pk_mul_f32 v[138:139], v[234:235], v[234:235]
	v_pk_mul_f32 v[140:141], v[236:237], v[236:237]
	v_pk_mul_f32 v[142:143], v[238:239], v[238:239]
	v_pk_mul_f32 v[144:145], v[240:241], v[240:241]
	v_pk_fma_f32 v[138:139], v[138:139], v[134:135], v[136:137]
	v_pk_fma_f32 v[140:141], v[140:141], v[134:135], v[136:137]
	v_pk_fma_f32 v[142:143], v[142:143], v[134:135], v[136:137]
	v_pk_fma_f32 v[144:145], v[144:145], v[134:135], v[136:137]
	v_pk_mul_f32 v[138:139], v[234:235], v[138:139]
	v_pk_mul_f32 v[140:141], v[236:237], v[140:141]
	v_pk_mul_f32 v[142:143], v[238:239], v[142:143]
	v_pk_mul_f32 v[144:145], v[240:241], v[144:145]
	v_exp_f32_e32 v138, v138
	v_exp_f32_e32 v139, v139
	v_exp_f32_e32 v140, v140
	v_exp_f32_e32 v141, v141
	v_exp_f32_e32 v142, v142
	v_exp_f32_e32 v143, v143
	v_exp_f32_e32 v144, v144
	v_exp_f32_e32 v145, v145
	v_pk_mul_f32 v[146:147], v[234:235], v[242:243]
	v_pk_mul_f32 v[148:149], v[236:237], v[244:245]
	v_pk_mul_f32 v[150:151], v[238:239], v[246:247]
	v_pk_mul_f32 v[152:153], v[240:241], v[248:249]
	v_pk_add_f32 v[138:139], v[138:139], 1.0 op_sel_hi:[1,0]
	v_pk_add_f32 v[140:141], v[140:141], 1.0 op_sel_hi:[1,0]
	v_pk_add_f32 v[142:143], v[142:143], 1.0 op_sel_hi:[1,0]
	v_pk_add_f32 v[144:145], v[144:145], 1.0 op_sel_hi:[1,0]
	v_rcp_f32_e32 v138, v138
	v_rcp_f32_e32 v139, v139
	v_rcp_f32_e32 v140, v140
	v_rcp_f32_e32 v141, v141
	v_rcp_f32_e32 v142, v142
	v_rcp_f32_e32 v143, v143
	v_rcp_f32_e32 v144, v144
	v_rcp_f32_e32 v145, v145
	v_pk_mul_f32 v[146:147], v[146:147], v[138:139]
	v_pk_mul_f32 v[148:149], v[148:149], v[140:141]
	v_pk_mul_f32 v[150:151], v[150:151], v[142:143]
	v_pk_mul_f32 v[152:153], v[152:153], v[144:145]
	v_cvt_pk_bf16_f32 v220, v146, v147
	v_cvt_pk_bf16_f32 v224, v148, v149
	v_cvt_pk_bf16_f32 v228, v150, v151
	v_cvt_pk_bf16_f32 v232, v152, v153
	s_waitcnt lgkmcnt(0)
;     __device__ __forceinline__ void operator()(const f32x4 (&acc)[2][2][4][2], const Unit& u) const {
;     ...
;                     for (int ep = 0; ep < 2; ++ep) {
;                         f32x2 cres[2][4];
; #pragma unroll
;                         for (int part = 0; part < 2; ++part) {
;                             const f32x2 w0 = (f32x2){W[part][0][2 * ep], W[part][0][2 * ep + 1]}, w1 = (f32x2){W[part][1][2 * ep], W[part][1][2 * ep + 1]};
;                             const f32x2 w2 = (f32x2){W[part][2][2 * ep], W[part][2][2 * ep + 1]}, bb = (f32x2){W[part][3][2 * ep], W[part][3][2 * ep + 1]};
;                             const f32x2 w0a = w0 * n0, w0b = w0 * m0, w2a = w2 * n15, w2b = w2 * m15;
;                             f32x2 X[4], R[4], L[4];
; #pragma unroll
;                             for (int m = 0; m < 4; ++m) { X[m] = (f32x2){acc[ai][part][m][n][2 * ep], acc[ai][part][m][n][2 * ep + 1]};
;                                 R[m] = (f32x2){dpp_prev(X[m].x), dpp_prev(X[m].y)}; L[m] = (f32x2){dpp_next(X[m].x), dpp_next(X[m].y)}; }
; #pragma unroll
;                             for (int m = 0; m < 4; ++m) {
;                                 f32x2 c = X[m] * w1 + bb; c = R[m] * w0a + c; c = L[m] * w2a + c;
;                                 if (m > 0) c = R[m > 0 ? m - 1 : 0] * w0b + c;
;                                 if (m < 3) c = L[m < 3 ? m + 1 : 3] * w2b + c;
;                                 cres[part][m] = c;
;                             }
;                             pe[0][part][n * 2 + ep] = cvt_pk_bf16(cres[part][0].x, cres[part][0].y);
;                             pe[1][part][n * 2 + ep] = cvt_pk_bf16(cres[part][3].x, cres[part][3].y);
;                             __builtin_amdgcn_sched_barrier(0);
;                         }
; #pragma unroll
;                         for (int m = 0; m < 4; ++m) {
;                             const f32x2 a = cres[0][m], v = cres[1][m];
;                             const f32x2 t = (a * a) * (-0.10294324f) + (-2.3022082f), z = a * t;
;                             f32x2 d; d.x = __builtin_amdgcn_exp2f(z.x) + 1.f; d.y = __builtin_amdgcn_exp2f(z.y) + 1.f;
;                             f32x2 r; r.x = __builtin_amdgcn_rcpf(d.x); r.y = __builtin_amdgcn_rcpf(d.y);
;                             const f32x2 o = (a * v) * r;
;                             gq[m][n * 2 + ep] = cvt_pk_bf16(o.x, o.y);
	v_pk_fma_f32 v[234:235], v[58:59], v[206:207], v[214:215]
	v_pk_fma_f32 v[236:237], v[34:35], v[206:207], v[214:215]
	v_pk_fma_f32 v[238:239], v[18:19], v[206:207], v[214:215]
	v_pk_fma_f32 v[240:241], v[2:3], v[206:207], v[214:215]
	v_pk_fma_f32 v[236:237], v[58:59], v[202:203], v[236:237]
	v_pk_fma_f32 v[238:239], v[34:35], v[202:203], v[238:239]
	v_pk_fma_f32 v[240:241], v[18:19], v[202:203], v[240:241]
	v_fmac_f32_dpp v234, v2, v202 row_shr:1 row_mask:0xf bank_mask:0xf bound_ctrl:1
	v_fmac_f32_dpp v235, v3, v203 row_shr:1 row_mask:0xf bank_mask:0xf bound_ctrl:1
	v_pk_fma_f32 v[236:237], v[18:19], v[210:211], v[236:237]
	v_pk_fma_f32 v[238:239], v[2:3], v[210:211], v[238:239]
	v_pk_fma_f32 v[234:235], v[34:35], v[210:211], v[234:235]
	v_fmac_f32_dpp v240, v58, v210 row_shl:1 row_mask:0xf bank_mask:0xf bound_ctrl:1
	v_fmac_f32_dpp v241, v59, v211 row_shl:1 row_mask:0xf bank_mask:0xf bound_ctrl:1
	v_cvt_pk_bf16_f32 v187, v234, v235
	v_cvt_pk_bf16_f32 v195, v240, v241
	v_pk_fma_f32 v[242:243], v[74:75], v[208:209], v[216:217]
	v_pk_fma_f32 v[244:245], v[42:43], v[208:209], v[216:217]
	v_pk_fma_f32 v[246:247], v[26:27], v[208:209], v[216:217]
	v_pk_fma_f32 v[248:249], v[10:11], v[208:209], v[216:217]
	v_pk_fma_f32 v[244:245], v[74:75], v[204:205], v[244:245]
	v_pk_fma_f32 v[246:247], v[42:43], v[204:205], v[246:247]
	v_pk_fma_f32 v[248:249], v[26:27], v[204:205], v[248:249]
	v_fmac_f32_dpp v242, v10, v204 row_shr:1 row_mask:0xf bank_mask:0xf bound_ctrl:1
	v_fmac_f32_dpp v243, v11, v205 row_shr:1 row_mask:0xf bank_mask:0xf bound_ctrl:1
	v_pk_fma_f32 v[244:245], v[26:27], v[212:213], v[244:245]
	v_pk_fma_f32 v[246:247], v[10:11], v[212:213], v[246:247]
	v_pk_fma_f32 v[242:243], v[42:43], v[212:213], v[242:243]
	v_fmac_f32_dpp v248, v74, v212 row_shl:1 row_mask:0xf bank_mask:0xf bound_ctrl:1
	v_fmac_f32_dpp v249, v75, v213 row_shl:1 row_mask:0xf bank_mask:0xf bound_ctrl:1
	v_cvt_pk_bf16_f32 v191, v242, v243
	v_cvt_pk_bf16_f32 v157, v248, v249
	v_pk_mul_f32 v[138:139], v[234:235], v[234:235]
	v_pk_mul_f32 v[140:141], v[236:237], v[236:237]
	v_pk_mul_f32 v[142:143], v[238:239], v[238:239]
	v_pk_mul_f32 v[144:145], v[240:241], v[240:241]
	v_pk_fma_f32 v[138:139], v[138:139], v[134:135], v[136:137]
	v_pk_fma_f32 v[140:141], v[140:141], v[134:135], v[136:137]
	v_pk_fma_f32 v[142:143], v[142:143], v[134:135], v[136:137]
	v_pk_fma_f32 v[144:145], v[144:145], v[134:135], v[136:137]
	v_pk_mul_f32 v[138:139], v[234:235], v[138:139]
	v_pk_mul_f32 v[140:141], v[236:237], v[140:141]
	v_pk_mul_f32 v[142:143], v[238:239], v[142:143]
	v_pk_mul_f32 v[144:145], v[240:241], v[144:145]
	v_exp_f32_e32 v138, v138
	v_exp_f32_e32 v139, v139
	v_exp_f32_e32 v140, v140
	v_exp_f32_e32 v141, v141
	v_exp_f32_e32 v142, v142
	v_exp_f32_e32 v143, v143
	v_exp_f32_e32 v144, v144
	v_exp_f32_e32 v145, v145
	v_pk_mul_f32 v[146:147], v[234:235], v[242:243]
	v_pk_mul_f32 v[148:149], v[236:237], v[244:245]
	v_pk_mul_f32 v[150:151], v[238:239], v[246:247]
	v_pk_mul_f32 v[152:153], v[240:241], v[248:249]
	v_pk_add_f32 v[138:139], v[138:139], 1.0 op_sel_hi:[1,0]
	v_pk_add_f32 v[140:141], v[140:141], 1.0 op_sel_hi:[1,0]
	v_pk_add_f32 v[142:143], v[142:143], 1.0 op_sel_hi:[1,0]
	v_pk_add_f32 v[144:145], v[144:145], 1.0 op_sel_hi:[1,0]
	v_rcp_f32_e32 v138, v138
	v_rcp_f32_e32 v139, v139
	v_rcp_f32_e32 v140, v140
	v_rcp_f32_e32 v141, v141
	v_rcp_f32_e32 v142, v142
	v_rcp_f32_e32 v143, v143
	v_rcp_f32_e32 v144, v144
	v_rcp_f32_e32 v145, v145
	v_pk_mul_f32 v[146:147], v[146:147], v[138:139]
	v_pk_mul_f32 v[148:149], v[148:149], v[140:141]
	v_pk_mul_f32 v[150:151], v[150:151], v[142:143]
	v_pk_mul_f32 v[152:153], v[152:153], v[144:145]
	v_cvt_pk_bf16_f32 v221, v146, v147
	v_cvt_pk_bf16_f32 v225, v148, v149
	v_cvt_pk_bf16_f32 v229, v150, v151
	v_cvt_pk_bf16_f32 v233, v152, v153
	s_mov_b64 s[22:23], exec
	s_mov_b64 exec, s[6:7]
	v_cvt_pk_bf16_f32 v138, v64, v65
	v_cvt_pk_bf16_f32 v139, v66, v67
	v_cvt_pk_bf16_f32 v140, v56, v57
	v_cvt_pk_bf16_f32 v141, v58, v59
	v_cvt_pk_bf16_f32 v142, v76, v77
	v_cvt_pk_bf16_f32 v143, v78, v79
	v_cvt_pk_bf16_f32 v144, v72, v73
	v_cvt_pk_bf16_f32 v145, v74, v75
	global_store_dwordx4 v129, v[138:141], s[10:11]
	global_store_dwordx4 v129, v[142:145], s[10:11] offset:16
	global_store_dwordx4 v129, v[184:187], s[10:11] offset:32
	global_store_dwordx4 v129, v[188:191], s[10:11] offset:48
	s_mov_b64 exec, s[8:9]
	v_cvt_pk_bf16_f32 v146, v4, v5
	v_cvt_pk_bf16_f32 v147, v6, v7
	v_cvt_pk_bf16_f32 v148, v0, v1
	v_cvt_pk_bf16_f32 v149, v2, v3
	v_cvt_pk_bf16_f32 v150, v12, v13
	v_cvt_pk_bf16_f32 v151, v14, v15
	v_cvt_pk_bf16_f32 v152, v8, v9
	v_cvt_pk_bf16_f32 v153, v10, v11
	global_store_dwordx4 v162, v[146:149], s[10:11]
	global_store_dwordx4 v162, v[150:153], s[10:11] offset:16
	global_store_dwordx4 v162, v[192:195], s[10:11] offset:32
	global_store_dwordx4 v162, v[154:157], s[10:11] offset:48
	s_mov_b64 exec, s[56:57]
	global_store_dwordx4 v128, v[218:221], s[52:53]
	s_mov_b64 exec, s[22:23]
	v_add_u32_e32 v133, 0x1600, v128
	v_add_u32_e32 v130, 0x2c00, v128
	v_add_u32_e32 v131, 0x4200, v128
	global_store_dwordx4 v133, v[222:225], s[52:53]
	global_store_dwordx4 v130, v[226:229], s[52:53]
	s_mov_b64 exec, s[58:59]
	global_store_dwordx4 v131, v[230:233], s[52:53]
	s_mov_b64 exec, s[22:23]
	s_mov_b64 s[8:9], 0
